# P0 weight f32->bf16 transposition loop rewritten by hand: 64x64 items, 64 row loads in flight, single LDS round trip
# baseline (speedup 1.0000x reference)
.LBB0_87:
	s_cmp_gt_i32 s2, 7
	s_cselect_b64 s[24:25], -1, 0
	s_xor_b64 s[26:27], s[0:1], -1
	s_or_b64 s[24:25], s[24:25], s[26:27]
	s_mov_b64 s[42:43], -1
	s_and_b64 vcc, exec, s[24:25]
	s_cbranch_vccz .LBB0_135
	s_and_b64 s[0:1], exec, s[0:1]
	s_cselect_b32 s5, 8, 0
	s_sub_i32 s0, s2, s5
	s_lshl_b32 s15, s0, 3
	s_add_i32 s15, s15, s88
	s_cmpk_gt_i32 s15, 0x5fff
	s_mov_b32 s1, 0
	s_cbranch_scc1 .LBB0_115
	s_mul_i32 s0, s88, 0x4100
	v_lshlrev_b32_e32 v236, 2, v86
	v_add_u32_e32 v237, s0, v236
	v_and_b32_e32 v240, 7, v86
	v_lshrrev_b32_e32 v241, 3, v86
	v_mul_u32_u24_e32 v238, 0x820, v240
	v_lshl_add_u32 v238, v241, 2, v238
	v_add_u32_e32 v238, s0, v238
	v_lshlrev_b32_e32 v242, 5, v240
	v_lshlrev_b32_e32 v240, 4, v240
	s_sub_i32 s0, s3, s5
	s_lshl_b32 s56, s0, 3
	s_mov_b32 s54, s15
	s_cmpk_gt_i32 s54, 0x2fff
	s_cbranch_scc1 .Lp0t_done
.Lp0t_loop:
	s_cmpk_lt_u32 s54, 0xa00
	s_cbranch_scc0 .Lp0t_m1
	s_mov_b32 s55, s54
	s_mul_i32 s0, s55, 0xcccd
	s_lshr_b32 s52, s0, 22
	s_mul_i32 s0, s52, 80
	s_sub_i32 s53, s55, s0
	s_mov_b32 s60, 0x5000
	s_mov_b32 s61, 0x1000
	s_mov_b64 s[46:47], s[34:35]
	s_add_u32 s62, s12, 0x200000
	s_addc_u32 s63, s13, 0
	s_mov_b32 s66, 0
	s_branch .Lp0t_go
.Lp0t_m1:
	s_cmpk_lt_u32 s54, 0xe00
	s_cbranch_scc0 .Lp0t_m2
	s_sub_i32 s55, s54, 0xa00
	s_lshr_b32 s52, s55, 5
	s_and_b32 s53, s55, 0x1f
	s_mov_b32 s60, 0x2000
	s_mov_b32 s61, 0x1000
	s_mov_b64 s[46:47], s[36:37]
	s_add_u32 s62, s12, 0x1600000
	s_addc_u32 s63, s13, 0
	s_mov_b32 s66, 0
	s_branch .Lp0t_go
.Lp0t_m2:
	s_cmpk_lt_u32 s54, 0xf00
	s_cbranch_scc0 .Lp0t_m3
	s_sub_i32 s55, s54, 0xe00
	s_lshr_b32 s52, s55, 3
	s_and_b32 s53, s55, 0x7
	s_mov_b32 s60, 0x800
	s_mov_b32 s61, 0x1000
	s_mov_b64 s[46:47], s[30:31]
	s_add_u32 s62, s12, 0x1e00000
	s_addc_u32 s63, s13, 0
	s_mov_b64 s[64:65], s[20:21]
	s_mov_b32 s66, 1
	s_branch .Lp0t_go
.Lp0t_m3:
	s_cmpk_lt_u32 s54, 0x1000
	s_cbranch_scc0 .Lp0t_m4
	s_sub_i32 s55, s54, 0xf00
	s_lshr_b32 s52, s55, 5
	s_and_b32 s53, s55, 0x1f
	s_mov_b32 s60, 0x2000
	s_mov_b32 s61, 0x400
	s_mov_b64 s[46:47], s[38:39]
	s_add_u32 s62, s12, 0x2400000
	s_addc_u32 s63, s13, 0
	s_mov_b32 s66, 0
	s_branch .Lp0t_go
.Lp0t_m4:
	s_cmpk_lt_u32 s54, 0x2000
	s_cbranch_scc0 .Lp0t_m5
	s_sub_i32 s55, s54, 0x1000
	s_lshr_b32 s52, s55, 7
	s_and_b32 s53, s55, 0x7f
	s_mov_b32 s60, 0x8000
	s_mov_b32 s61, 0x1000
	s_mov_b64 s[46:47], s[28:29]
	s_add_u32 s62, s12, 0x2600000
	s_addc_u32 s63, s13, 0
	s_mov_b64 s[64:65], s[22:23]
	s_mov_b32 s66, 1
	s_branch .Lp0t_go
.Lp0t_m5:
	s_sub_i32 s55, s54, 0x2000
	s_lshr_b32 s52, s55, 5
	s_and_b32 s53, s55, 0x1f
	s_mov_b32 s60, 0x2000
	s_mov_b32 s61, 0x4000
	s_mov_b64 s[46:47], s[40:41]
	s_add_u32 s62, s12, 0x4600000
	s_addc_u32 s63, s13, 0
	s_mov_b32 s66, 0
	s_branch .Lp0t_go
.Lp0t_go:
	s_lshl_b32 s0, s60, 6
	s_mul_i32 s0, s52, s0
	s_lshl_b32 s1, s53, 8
	s_add_u32 s0, s0, s1
	s_add_u32 s48, s46, s0
	s_addc_u32 s49, s47, 0
	s_lshl_b32 s0, s61, 6
	s_mul_i32 s0, s53, s0
	s_lshl_b32 s1, s52, 7
	s_add_u32 s0, s0, s1
	s_add_u32 s50, s62, s0
	s_addc_u32 s51, s63, 0
	v_mul_lo_u32 v239, v241, s61
	v_add_u32_e32 v239, v239, v240
	s_cmp_eq_u32 s66, 0
	s_cbranch_scc1 .Lp0t_nogk1
	s_lshl_b32 s0, s52, 8
	s_add_u32 s64, s64, s0
	s_addc_u32 s65, s65, 0
	global_load_dwordx4 v[228:231], v242, s[64:65]
	global_load_dwordx4 v[232:235], v242, s[64:65] offset:16
.Lp0t_nogk1:
	global_load_dword v100, v236, s[48:49]
	s_add_u32 s48, s48, s60
	s_addc_u32 s49, s49, 0
	global_load_dword v101, v236, s[48:49]
	s_add_u32 s48, s48, s60
	s_addc_u32 s49, s49, 0
	global_load_dword v102, v236, s[48:49]
	s_add_u32 s48, s48, s60
	s_addc_u32 s49, s49, 0
	global_load_dword v103, v236, s[48:49]
	s_add_u32 s48, s48, s60
	s_addc_u32 s49, s49, 0
	global_load_dword v104, v236, s[48:49]
	s_add_u32 s48, s48, s60
	s_addc_u32 s49, s49, 0
	global_load_dword v105, v236, s[48:49]
	s_add_u32 s48, s48, s60
	s_addc_u32 s49, s49, 0
	global_load_dword v106, v236, s[48:49]
	s_add_u32 s48, s48, s60
	s_addc_u32 s49, s49, 0
	global_load_dword v107, v236, s[48:49]
	s_add_u32 s48, s48, s60
	s_addc_u32 s49, s49, 0
	global_load_dword v108, v236, s[48:49]
	s_add_u32 s48, s48, s60
	s_addc_u32 s49, s49, 0
	global_load_dword v109, v236, s[48:49]
	s_add_u32 s48, s48, s60
	s_addc_u32 s49, s49, 0
	global_load_dword v110, v236, s[48:49]
	s_add_u32 s48, s48, s60
	s_addc_u32 s49, s49, 0
	global_load_dword v111, v236, s[48:49]
	s_add_u32 s48, s48, s60
	s_addc_u32 s49, s49, 0
	global_load_dword v112, v236, s[48:49]
	s_add_u32 s48, s48, s60
	s_addc_u32 s49, s49, 0
	global_load_dword v113, v236, s[48:49]
	s_add_u32 s48, s48, s60
	s_addc_u32 s49, s49, 0
	global_load_dword v114, v236, s[48:49]
	s_add_u32 s48, s48, s60
	s_addc_u32 s49, s49, 0
	global_load_dword v115, v236, s[48:49]
	s_add_u32 s48, s48, s60
	s_addc_u32 s49, s49, 0
	global_load_dword v116, v236, s[48:49]
	s_add_u32 s48, s48, s60
	s_addc_u32 s49, s49, 0
	global_load_dword v117, v236, s[48:49]
	s_add_u32 s48, s48, s60
	s_addc_u32 s49, s49, 0
	global_load_dword v118, v236, s[48:49]
	s_add_u32 s48, s48, s60
	s_addc_u32 s49, s49, 0
	global_load_dword v119, v236, s[48:49]
	s_add_u32 s48, s48, s60
	s_addc_u32 s49, s49, 0
	global_load_dword v120, v236, s[48:49]
	s_add_u32 s48, s48, s60
	s_addc_u32 s49, s49, 0
	global_load_dword v121, v236, s[48:49]
	s_add_u32 s48, s48, s60
	s_addc_u32 s49, s49, 0
	global_load_dword v122, v236, s[48:49]
	s_add_u32 s48, s48, s60
	s_addc_u32 s49, s49, 0
	global_load_dword v123, v236, s[48:49]
	s_add_u32 s48, s48, s60
	s_addc_u32 s49, s49, 0
	global_load_dword v124, v236, s[48:49]
	s_add_u32 s48, s48, s60
	s_addc_u32 s49, s49, 0
	global_load_dword v125, v236, s[48:49]
	s_add_u32 s48, s48, s60
	s_addc_u32 s49, s49, 0
	global_load_dword v126, v236, s[48:49]
	s_add_u32 s48, s48, s60
	s_addc_u32 s49, s49, 0
	global_load_dword v127, v236, s[48:49]
	s_add_u32 s48, s48, s60
	s_addc_u32 s49, s49, 0
	global_load_dword v128, v236, s[48:49]
	s_add_u32 s48, s48, s60
	s_addc_u32 s49, s49, 0
	global_load_dword v129, v236, s[48:49]
	s_add_u32 s48, s48, s60
	s_addc_u32 s49, s49, 0
	global_load_dword v130, v236, s[48:49]
	s_add_u32 s48, s48, s60
	s_addc_u32 s49, s49, 0
	global_load_dword v131, v236, s[48:49]
	s_add_u32 s48, s48, s60
	s_addc_u32 s49, s49, 0
	global_load_dword v132, v236, s[48:49]
	s_add_u32 s48, s48, s60
	s_addc_u32 s49, s49, 0
	global_load_dword v133, v236, s[48:49]
	s_add_u32 s48, s48, s60
	s_addc_u32 s49, s49, 0
	global_load_dword v134, v236, s[48:49]
	s_add_u32 s48, s48, s60
	s_addc_u32 s49, s49, 0
	global_load_dword v135, v236, s[48:49]
	s_add_u32 s48, s48, s60
	s_addc_u32 s49, s49, 0
	global_load_dword v136, v236, s[48:49]
	s_add_u32 s48, s48, s60
	s_addc_u32 s49, s49, 0
	global_load_dword v137, v236, s[48:49]
	s_add_u32 s48, s48, s60
	s_addc_u32 s49, s49, 0
	global_load_dword v138, v236, s[48:49]
	s_add_u32 s48, s48, s60
	s_addc_u32 s49, s49, 0
	global_load_dword v139, v236, s[48:49]
	s_add_u32 s48, s48, s60
	s_addc_u32 s49, s49, 0
	global_load_dword v140, v236, s[48:49]
	s_add_u32 s48, s48, s60
	s_addc_u32 s49, s49, 0
	global_load_dword v141, v236, s[48:49]
	s_add_u32 s48, s48, s60
	s_addc_u32 s49, s49, 0
	global_load_dword v142, v236, s[48:49]
	s_add_u32 s48, s48, s60
	s_addc_u32 s49, s49, 0
	global_load_dword v143, v236, s[48:49]
	s_add_u32 s48, s48, s60
	s_addc_u32 s49, s49, 0
	global_load_dword v144, v236, s[48:49]
	s_add_u32 s48, s48, s60
	s_addc_u32 s49, s49, 0
	global_load_dword v145, v236, s[48:49]
	s_add_u32 s48, s48, s60
	s_addc_u32 s49, s49, 0
	global_load_dword v146, v236, s[48:49]
	s_add_u32 s48, s48, s60
	s_addc_u32 s49, s49, 0
	global_load_dword v147, v236, s[48:49]
	s_add_u32 s48, s48, s60
	s_addc_u32 s49, s49, 0
	global_load_dword v148, v236, s[48:49]
	s_add_u32 s48, s48, s60
	s_addc_u32 s49, s49, 0
	global_load_dword v149, v236, s[48:49]
	s_add_u32 s48, s48, s60
	s_addc_u32 s49, s49, 0
	global_load_dword v150, v236, s[48:49]
	s_add_u32 s48, s48, s60
	s_addc_u32 s49, s49, 0
	global_load_dword v151, v236, s[48:49]
	s_add_u32 s48, s48, s60
	s_addc_u32 s49, s49, 0
	global_load_dword v152, v236, s[48:49]
	s_add_u32 s48, s48, s60
	s_addc_u32 s49, s49, 0
	global_load_dword v153, v236, s[48:49]
	s_add_u32 s48, s48, s60
	s_addc_u32 s49, s49, 0
	global_load_dword v154, v236, s[48:49]
	s_add_u32 s48, s48, s60
	s_addc_u32 s49, s49, 0
	global_load_dword v155, v236, s[48:49]
	s_add_u32 s48, s48, s60
	s_addc_u32 s49, s49, 0
	global_load_dword v156, v236, s[48:49]
	s_add_u32 s48, s48, s60
	s_addc_u32 s49, s49, 0
	global_load_dword v157, v236, s[48:49]
	s_add_u32 s48, s48, s60
	s_addc_u32 s49, s49, 0
	global_load_dword v158, v236, s[48:49]
	s_add_u32 s48, s48, s60
	s_addc_u32 s49, s49, 0
	global_load_dword v159, v236, s[48:49]
	s_add_u32 s48, s48, s60
	s_addc_u32 s49, s49, 0
	global_load_dword v160, v236, s[48:49]
	s_add_u32 s48, s48, s60
	s_addc_u32 s49, s49, 0
	global_load_dword v161, v236, s[48:49]
	s_add_u32 s48, s48, s60
	s_addc_u32 s49, s49, 0
	global_load_dword v162, v236, s[48:49]
	s_add_u32 s48, s48, s60
	s_addc_u32 s49, s49, 0
	global_load_dword v163, v236, s[48:49]
	s_waitcnt vmcnt(56)
	ds_write_b32 v237, v100 offset:0
	ds_write_b32 v237, v101 offset:260
	ds_write_b32 v237, v102 offset:520
	ds_write_b32 v237, v103 offset:780
	ds_write_b32 v237, v104 offset:1040
	ds_write_b32 v237, v105 offset:1300
	ds_write_b32 v237, v106 offset:1560
	ds_write_b32 v237, v107 offset:1820
	s_waitcnt vmcnt(48)
	ds_write_b32 v237, v108 offset:2080
	ds_write_b32 v237, v109 offset:2340
	ds_write_b32 v237, v110 offset:2600
	ds_write_b32 v237, v111 offset:2860
	ds_write_b32 v237, v112 offset:3120
	ds_write_b32 v237, v113 offset:3380
	ds_write_b32 v237, v114 offset:3640
	ds_write_b32 v237, v115 offset:3900
	s_waitcnt vmcnt(40)
	ds_write_b32 v237, v116 offset:4160
	ds_write_b32 v237, v117 offset:4420
	ds_write_b32 v237, v118 offset:4680
	ds_write_b32 v237, v119 offset:4940
	ds_write_b32 v237, v120 offset:5200
	ds_write_b32 v237, v121 offset:5460
	ds_write_b32 v237, v122 offset:5720
	ds_write_b32 v237, v123 offset:5980
	s_waitcnt vmcnt(32)
	ds_write_b32 v237, v124 offset:6240
	ds_write_b32 v237, v125 offset:6500
	ds_write_b32 v237, v126 offset:6760
	ds_write_b32 v237, v127 offset:7020
	ds_write_b32 v237, v128 offset:7280
	ds_write_b32 v237, v129 offset:7540
	ds_write_b32 v237, v130 offset:7800
	ds_write_b32 v237, v131 offset:8060
	s_waitcnt vmcnt(24)
	ds_write_b32 v237, v132 offset:8320
	ds_write_b32 v237, v133 offset:8580
	ds_write_b32 v237, v134 offset:8840
	ds_write_b32 v237, v135 offset:9100
	ds_write_b32 v237, v136 offset:9360
	ds_write_b32 v237, v137 offset:9620
	ds_write_b32 v237, v138 offset:9880
	ds_write_b32 v237, v139 offset:10140
	s_waitcnt vmcnt(16)
	ds_write_b32 v237, v140 offset:10400
	ds_write_b32 v237, v141 offset:10660
	ds_write_b32 v237, v142 offset:10920
	ds_write_b32 v237, v143 offset:11180
	ds_write_b32 v237, v144 offset:11440
	ds_write_b32 v237, v145 offset:11700
	ds_write_b32 v237, v146 offset:11960
	ds_write_b32 v237, v147 offset:12220
	s_waitcnt vmcnt(8)
	ds_write_b32 v237, v148 offset:12480
	ds_write_b32 v237, v149 offset:12740
	ds_write_b32 v237, v150 offset:13000
	ds_write_b32 v237, v151 offset:13260
	ds_write_b32 v237, v152 offset:13520
	ds_write_b32 v237, v153 offset:13780
	ds_write_b32 v237, v154 offset:14040
	ds_write_b32 v237, v155 offset:14300
	s_waitcnt vmcnt(0)
	ds_write_b32 v237, v156 offset:14560
	ds_write_b32 v237, v157 offset:14820
	ds_write_b32 v237, v158 offset:15080
	ds_write_b32 v237, v159 offset:15340
	ds_write_b32 v237, v160 offset:15600
	ds_write_b32 v237, v161 offset:15860
	ds_write_b32 v237, v162 offset:16120
	ds_write_b32 v237, v163 offset:16380
	s_waitcnt lgkmcnt(0)
	ds_read_b32 v164, v238 offset:0
	ds_read_b32 v165, v238 offset:260
	ds_read_b32 v166, v238 offset:520
	ds_read_b32 v167, v238 offset:780
	ds_read_b32 v168, v238 offset:1040
	ds_read_b32 v169, v238 offset:1300
	ds_read_b32 v170, v238 offset:1560
	ds_read_b32 v171, v238 offset:1820
	ds_read_b32 v172, v238 offset:32
	ds_read_b32 v173, v238 offset:292
	ds_read_b32 v174, v238 offset:552
	ds_read_b32 v175, v238 offset:812
	ds_read_b32 v176, v238 offset:1072
	ds_read_b32 v177, v238 offset:1332
	ds_read_b32 v178, v238 offset:1592
	ds_read_b32 v179, v238 offset:1852
	ds_read_b32 v180, v238 offset:64
	ds_read_b32 v181, v238 offset:324
	ds_read_b32 v182, v238 offset:584
	ds_read_b32 v183, v238 offset:844
	ds_read_b32 v184, v238 offset:1104
	ds_read_b32 v185, v238 offset:1364
	ds_read_b32 v186, v238 offset:1624
	ds_read_b32 v187, v238 offset:1884
	ds_read_b32 v188, v238 offset:96
	ds_read_b32 v189, v238 offset:356
	ds_read_b32 v190, v238 offset:616
	ds_read_b32 v191, v238 offset:876
	ds_read_b32 v192, v238 offset:1136
	ds_read_b32 v193, v238 offset:1396
	ds_read_b32 v194, v238 offset:1656
	ds_read_b32 v195, v238 offset:1916
	ds_read_b32 v196, v238 offset:128
	ds_read_b32 v197, v238 offset:388
	ds_read_b32 v198, v238 offset:648
	ds_read_b32 v199, v238 offset:908
	ds_read_b32 v200, v238 offset:1168
	ds_read_b32 v201, v238 offset:1428
	ds_read_b32 v202, v238 offset:1688
	ds_read_b32 v203, v238 offset:1948
	ds_read_b32 v204, v238 offset:160
	ds_read_b32 v205, v238 offset:420
	ds_read_b32 v206, v238 offset:680
	ds_read_b32 v207, v238 offset:940
	ds_read_b32 v208, v238 offset:1200
	ds_read_b32 v209, v238 offset:1460
	ds_read_b32 v210, v238 offset:1720
	ds_read_b32 v211, v238 offset:1980
	ds_read_b32 v212, v238 offset:192
	ds_read_b32 v213, v238 offset:452
	ds_read_b32 v214, v238 offset:712
	ds_read_b32 v215, v238 offset:972
	ds_read_b32 v216, v238 offset:1232
	ds_read_b32 v217, v238 offset:1492
	ds_read_b32 v218, v238 offset:1752
	ds_read_b32 v219, v238 offset:2012
	ds_read_b32 v220, v238 offset:224
	ds_read_b32 v221, v238 offset:484
	ds_read_b32 v222, v238 offset:744
	ds_read_b32 v223, v238 offset:1004
	ds_read_b32 v224, v238 offset:1264
	ds_read_b32 v225, v238 offset:1524
	ds_read_b32 v226, v238 offset:1784
	ds_read_b32 v227, v238 offset:2044
	s_waitcnt lgkmcnt(0)
	s_cmp_eq_u32 s66, 0
	s_cbranch_scc1 .Lp0t_nogk2
	v_mul_f32_e32 v164, v164, v228
	v_mul_f32_e32 v165, v165, v229
	v_mul_f32_e32 v166, v166, v230
	v_mul_f32_e32 v167, v167, v231
	v_mul_f32_e32 v168, v168, v232
	v_mul_f32_e32 v169, v169, v233
	v_mul_f32_e32 v170, v170, v234
	v_mul_f32_e32 v171, v171, v235
	v_mul_f32_e32 v172, v172, v228
	v_mul_f32_e32 v173, v173, v229
	v_mul_f32_e32 v174, v174, v230
	v_mul_f32_e32 v175, v175, v231
	v_mul_f32_e32 v176, v176, v232
	v_mul_f32_e32 v177, v177, v233
	v_mul_f32_e32 v178, v178, v234
	v_mul_f32_e32 v179, v179, v235
	v_mul_f32_e32 v180, v180, v228
	v_mul_f32_e32 v181, v181, v229
	v_mul_f32_e32 v182, v182, v230
	v_mul_f32_e32 v183, v183, v231
	v_mul_f32_e32 v184, v184, v232
	v_mul_f32_e32 v185, v185, v233
	v_mul_f32_e32 v186, v186, v234
	v_mul_f32_e32 v187, v187, v235
	v_mul_f32_e32 v188, v188, v228
	v_mul_f32_e32 v189, v189, v229
	v_mul_f32_e32 v190, v190, v230
	v_mul_f32_e32 v191, v191, v231
	v_mul_f32_e32 v192, v192, v232
	v_mul_f32_e32 v193, v193, v233
	v_mul_f32_e32 v194, v194, v234
	v_mul_f32_e32 v195, v195, v235
	v_mul_f32_e32 v196, v196, v228
	v_mul_f32_e32 v197, v197, v229
	v_mul_f32_e32 v198, v198, v230
	v_mul_f32_e32 v199, v199, v231
	v_mul_f32_e32 v200, v200, v232
	v_mul_f32_e32 v201, v201, v233
	v_mul_f32_e32 v202, v202, v234
	v_mul_f32_e32 v203, v203, v235
	v_mul_f32_e32 v204, v204, v228
	v_mul_f32_e32 v205, v205, v229
	v_mul_f32_e32 v206, v206, v230
	v_mul_f32_e32 v207, v207, v231
	v_mul_f32_e32 v208, v208, v232
	v_mul_f32_e32 v209, v209, v233
	v_mul_f32_e32 v210, v210, v234
	v_mul_f32_e32 v211, v211, v235
	v_mul_f32_e32 v212, v212, v228
	v_mul_f32_e32 v213, v213, v229
	v_mul_f32_e32 v214, v214, v230
	v_mul_f32_e32 v215, v215, v231
	v_mul_f32_e32 v216, v216, v232
	v_mul_f32_e32 v217, v217, v233
	v_mul_f32_e32 v218, v218, v234
	v_mul_f32_e32 v219, v219, v235
	v_mul_f32_e32 v220, v220, v228
	v_mul_f32_e32 v221, v221, v229
	v_mul_f32_e32 v222, v222, v230
	v_mul_f32_e32 v223, v223, v231
	v_mul_f32_e32 v224, v224, v232
	v_mul_f32_e32 v225, v225, v233
	v_mul_f32_e32 v226, v226, v234
	v_mul_f32_e32 v227, v227, v235
.Lp0t_nogk2:
	v_cvt_pk_bf16_f32 v100, v164, v165
	v_cvt_pk_bf16_f32 v101, v166, v167
	v_cvt_pk_bf16_f32 v102, v168, v169
	v_cvt_pk_bf16_f32 v103, v170, v171
	v_cvt_pk_bf16_f32 v104, v172, v173
	v_cvt_pk_bf16_f32 v105, v174, v175
	v_cvt_pk_bf16_f32 v106, v176, v177
	v_cvt_pk_bf16_f32 v107, v178, v179
	v_cvt_pk_bf16_f32 v108, v180, v181
	v_cvt_pk_bf16_f32 v109, v182, v183
	v_cvt_pk_bf16_f32 v110, v184, v185
	v_cvt_pk_bf16_f32 v111, v186, v187
	v_cvt_pk_bf16_f32 v112, v188, v189
	v_cvt_pk_bf16_f32 v113, v190, v191
	v_cvt_pk_bf16_f32 v114, v192, v193
	v_cvt_pk_bf16_f32 v115, v194, v195
	v_cvt_pk_bf16_f32 v116, v196, v197
	v_cvt_pk_bf16_f32 v117, v198, v199
	v_cvt_pk_bf16_f32 v118, v200, v201
	v_cvt_pk_bf16_f32 v119, v202, v203
	v_cvt_pk_bf16_f32 v120, v204, v205
	v_cvt_pk_bf16_f32 v121, v206, v207
	v_cvt_pk_bf16_f32 v122, v208, v209
	v_cvt_pk_bf16_f32 v123, v210, v211
	v_cvt_pk_bf16_f32 v124, v212, v213
	v_cvt_pk_bf16_f32 v125, v214, v215
	v_cvt_pk_bf16_f32 v126, v216, v217
	v_cvt_pk_bf16_f32 v127, v218, v219
	v_cvt_pk_bf16_f32 v128, v220, v221
	v_cvt_pk_bf16_f32 v129, v222, v223
	v_cvt_pk_bf16_f32 v130, v224, v225
	v_cvt_pk_bf16_f32 v131, v226, v227
	s_lshl_b32 s0, s61, 3
	global_store_dwordx4 v239, v[100:103], s[50:51]
	s_add_u32 s50, s50, s0
	s_addc_u32 s51, s51, 0
	global_store_dwordx4 v239, v[104:107], s[50:51]
	s_add_u32 s50, s50, s0
	s_addc_u32 s51, s51, 0
	global_store_dwordx4 v239, v[108:111], s[50:51]
	s_add_u32 s50, s50, s0
	s_addc_u32 s51, s51, 0
	global_store_dwordx4 v239, v[112:115], s[50:51]
	s_add_u32 s50, s50, s0
	s_addc_u32 s51, s51, 0
	global_store_dwordx4 v239, v[116:119], s[50:51]
	s_add_u32 s50, s50, s0
	s_addc_u32 s51, s51, 0
	global_store_dwordx4 v239, v[120:123], s[50:51]
	s_add_u32 s50, s50, s0
	s_addc_u32 s51, s51, 0
	global_store_dwordx4 v239, v[124:127], s[50:51]
	s_add_u32 s50, s50, s0
	s_addc_u32 s51, s51, 0
	global_store_dwordx4 v239, v[128:131], s[50:51]
	s_add_i32 s54, s54, s56
	s_cmpk_gt_i32 s54, 0x2fff
	s_cbranch_scc0 .Lp0t_loop
.Lp0t_done:
	s_branch .LBB0_115
.LBB0_115:
	s_cmpk_gt_i32 s15, 0x7fff
	s_cbranch_scc1 .LBB0_134
	v_mov_b32_e32 v1, 0
	v_lshlrev_b32_e32 v0, 4, v86
	v_mov_b32_e32 v17, v1
	v_lshl_add_u64 v[68:69], s[16:17], 0, v[0:1]
	v_lshl_add_u64 v[70:71], s[18:19], 0, v[0:1]
	v_lshl_add_u64 v[0:1], s[12:13], 0, v[16:17]
	s_mov_b64 s[0:1], 0x7000000
	v_lshl_add_u64 v[72:73], v[0:1], 0, s[0:1]
	s_mov_b64 s[0:1], 0x1000
	v_lshl_add_u64 v[74:75], v[70:71], 0, s[0:1]
	s_mov_b64 s[0:1], 0x1400
	v_lshl_add_u64 v[76:77], v[70:71], 0, s[0:1]
	s_mov_b64 s[0:1], 0x1800
	v_lshl_add_u64 v[78:79], v[70:71], 0, s[0:1]
	s_mov_b64 s[0:1], 0x1c00
	v_lshl_add_u64 v[80:81], v[70:71], 0, s[0:1]
	s_lshl_b32 s0, s5, 3
	s_sub_i32 s15, 0, s0
	s_lshl_b32 s0, s3, 4
	s_lshl_b32 s1, s5, 4
	s_sub_i32 s20, s0, s1
	s_sub_i32 s21, s4, s1
	s_movk_i32 s22, 0x1000
	v_mov_b32_e32 v92, 0x358637bd
	s_mov_b32 s23, 0xf800000
	v_mov_b32_e32 v93, 0x260
	global_load_dwordx4 v[100:103], v[70:71], off
	global_load_dwordx4 v[104:107], v[70:71], off offset:1024
	global_load_dwordx4 v[108:111], v[70:71], off offset:2048
	global_load_dwordx4 v[112:115], v[70:71], off offset:3072
	global_load_dwordx4 v[116:119], v[74:75], off
	global_load_dwordx4 v[120:123], v[76:77], off
	global_load_dwordx4 v[124:127], v[78:79], off
	global_load_dwordx4 v[128:131], v[80:81], off
	s_branch .LBB0_118
